# v71 plus XCD-aware unit mapping in the memory-attention prompt units: the 16 query-tile units that share one (batch, head) K/V block run on one XCD (two groups per XCD) instead of two per XCD
# speedup vs baseline: 1.0067x; 1.0046x over previous
; #define LAS __attribute__((address_space(3)))
; template <bool SAMPLE>
; __device__ __forceinline__ void mem_unit(const Params& p, int l, LAS unsigned char* lds, int unit, int tid, int wave, int lane) {
;     const bf16* MQ = (const bf16*)(p.ws + W_MQ); bf16* MO = (bf16*)(p.ws + W_MO);
;     LAS bf16* Kl = (LAS bf16*)lds; LAS bf16* Vt = (LAS bf16*)(lds + MEM_VOFF);
;     int b, h, qt;
;     if (!SAMPLE) { qt = unit & 15; h = (unit >> 4) & 3; b = unit >> 6; } else { h = unit & 3; b = unit >> 2; qt = 0; }
; __global__ void __launch_bounds__(NTHR, 2) fwd_megakernel(Params p) {
;     ...
;         { PHASE_IDS
;         for (int rep = 0; rep < REP_LIGHT * REP_MEM; ++rep)
;         for (int u = bx; u < 256 + 512; u += G) { if (u < 256) mem_unit<false>(p, l, lds, u, tid, wave, lane); else mem_unit<true>(p, l, lds, u - 256, tid, wave, lane); } }
.LBB0_619:
	s_and_b64 vcc, exec, s[0:1]
	s_cbranch_vccz .LBB0_596
	s_and_b32 s100, s35, 7
	s_lshl_b32 s100, s100, 5
	s_lshr_b32 s101, s35, 3
	s_and_b32 s101, s101, 15
	s_or_b32 s100, s100, s101
	s_lshr_b32 s101, s35, 7
	s_lshl_b32 s101, s101, 4
	s_or_b32 s100, s100, s101
	s_nop 0
	s_nop 0
	s_nop 0
	s_nop 0
	s_nop 0
	s_nop 0
	s_nop 0
	s_nop 0
	s_nop 0
	global_load_dwordx4 v[0:3], v[86:87], off offset:16
	global_load_dwordx4 v[4:7], v[86:87], off
	v_and_b32_e32 v9, 64, v99
	v_xor_b32_e32 v8, 1, v99
	v_add_u32_e32 v92, 64, v9
	v_cmp_lt_i32_e32 vcc, v8, v92
	s_ashr_i32 s2, s100, 6
	s_lshl_b32 s16, s2, 8
	v_cndmask_b32_e32 v8, v99, v8, vcc
	v_lshlrev_b32_e32 v82, 2, v8
	v_xor_b32_e32 v8, 2, v99
	v_cmp_lt_i32_e32 vcc, v8, v92
	s_lshl_b32 s0, s100, 3
	s_and_b32 s1, s100, 15
	v_cndmask_b32_e32 v8, v99, v8, vcc
	v_lshlrev_b32_e32 v93, 2, v8
	v_xor_b32_e32 v8, 4, v99
	s_ashr_i32 s17, s16, 31
	s_and_b32 s36, s0, 0x180
	v_cmp_lt_i32_e32 vcc, v8, v92
	s_cmp_eq_u32 s1, 0
	s_cselect_b64 s[18:19], -1, 0
	v_cndmask_b32_e32 v8, v99, v8, vcc
	v_lshlrev_b32_e32 v100, 2, v8
	v_xor_b32_e32 v8, 8, v99
	s_ashr_i32 s3, s2, 31
	v_cmp_lt_i32_e32 vcc, v8, v92
	s_lshl_b64 s[8:9], s[2:3], 17
	s_or_b32 s1, s8, s36
	v_cndmask_b32_e32 v8, v99, v8, vcc
	s_lshl_b32 s10, s36, 2
	s_mov_b32 s0, 0
	v_lshlrev_b32_e32 v101, 2, v8
	s_waitcnt vmcnt(2)
	v_mov_b32_e32 v73, s9
	v_or_b32_e32 v72, s1, v80
	v_lshl_add_u64 v[74:75], v[84:85], 0, s[10:11]
	s_mov_b64 s[20:21], -1
	s_branch .LBB0_622

; template <bool SAMPLE>
; __device__ __forceinline__ void mem_unit(const Params& p, int l, LAS unsigned char* lds, int unit, int tid, int wave, int lane) {
;     ...
;         int q16 = lane & 15, kq = lane >> 4; asm volatile("" : "+v"(q16), "+v"(kq));
;         size_t row; bool st;
;         if (!SAMPLE) { row = (size_t)b * 8192 + (qt * 4 + qq) * 128 + 16 * wave + q16; st = true; } else { row = (size_t)MP + 8 * b + (q16 & 7); st = q16 < 8; }
.LBB0_630:
	s_and_b32 s0, s100, 15
	s_lshl_b32 s10, s0, 9
	s_lshl_b64 s[8:9], s[2:3], 13
	s_lshl_b32 s2, s36, 1
	s_add_u32 s0, s64, s2
	s_addc_u32 s1, s65, 0
	v_xor_b32_e32 v0, 16, v99
	s_add_u32 s2, s28, s2
	v_cmp_lt_i32_e32 vcc, v0, v92
	s_addc_u32 s3, s29, 0
	s_add_u32 s8, s6, s8
	v_cndmask_b32_e32 v0, v99, v0, vcc
	v_lshlrev_b32_e32 v82, 2, v0
	v_xor_b32_e32 v0, 32, v99
	v_cmp_lt_i32_e32 vcc, v0, v92
	s_addc_u32 s9, s7, s9
	s_add_u32 s10, s8, s10
	v_cndmask_b32_e32 v0, v99, v0, vcc
	v_lshlrev_b32_e32 v100, 2, v0
	s_addc_u32 s18, s9, 0
	s_mov_b64 s[8:9], 0
	s_waitcnt lgkmcnt(0)
	s_barrier

; #define LAS __attribute__((address_space(3)))
; template <bool SAMPLE>
; __device__ __forceinline__ void mem_unit(const Params& p, int l, LAS unsigned char* lds, int unit, int tid, int wave, int lane) {
;     const bf16* MQ = (const bf16*)(p.ws + W_MQ); bf16* MO = (bf16*)(p.ws + W_MO);
;     LAS bf16* Kl = (LAS bf16*)lds; LAS bf16* Vt = (LAS bf16*)(lds + MEM_VOFF);
;     int b, h, qt;
;     if (!SAMPLE) { qt = unit & 15; h = (unit >> 4) & 3; b = unit >> 6; } else { h = unit & 3; b = unit >> 2; qt = 0; }
;     {
;         const int sub = tid & 15;
;         float kg[8]; pg8::ld8f(p.in[I_MKG] + l * 128 + 8 * sub, kg);
; __global__ void __launch_bounds__(NTHR, 2) fwd_megakernel(Params p) {
;     ...
;         { PHASE_IDS
;         for (int rep = 0; rep < REP_LIGHT * REP_MEM; ++rep)
;         for (int u = bx; u < 256 + 512; u += G) { if (u < 256) mem_unit<false>(p, l, lds, u, tid, wave, lane); else mem_unit<true>(p, l, lds, u - 256, tid, wave, lane); } }
.LBB0_2750:
	s_and_b64 vcc, exec, s[0:1]
	s_cbranch_vccz .LBB0_2727
	s_and_b32 s100, s26, 7
	s_lshl_b32 s100, s100, 5
	s_lshr_b32 s101, s26, 3
	s_and_b32 s101, s101, 15
	s_or_b32 s100, s100, s101
	s_lshr_b32 s101, s26, 7
	s_lshl_b32 s101, s101, 4
	s_or_b32 s100, s100, s101
	s_nop 0
	s_nop 0
	s_nop 0
	s_nop 0
	s_nop 0
	s_nop 0
	s_nop 0
	s_nop 0
	s_nop 0
	global_load_dwordx4 v[0:3], v[86:87], off offset:528
	global_load_dwordx4 v[4:7], v[86:87], off offset:512
	v_and_b32_e32 v9, 64, v99
	s_ashr_i32 s2, s100, 6
	v_xor_b32_e32 v8, 1, v99
	v_add_u32_e32 v92, 64, v9
	s_lshl_b32 s0, s2, 8
	v_cmp_lt_i32_e32 vcc, v8, v92
	s_and_b32 s1, s100, 15
	s_ashr_i32 s3, s0, 31
	v_cndmask_b32_e32 v8, v99, v8, vcc
	s_add_u32 s16, s0, 0x400
	v_lshlrev_b32_e32 v82, 2, v8
	v_xor_b32_e32 v8, 2, v99
	s_addc_u32 s17, s3, 0
	s_lshl_b32 s0, s100, 3
	v_cmp_lt_i32_e32 vcc, v8, v92
	s_and_b32 s27, s0, 0x180
	s_cmp_eq_u32 s1, 0
	v_cndmask_b32_e32 v8, v99, v8, vcc
	v_lshlrev_b32_e32 v93, 2, v8
	v_xor_b32_e32 v8, 4, v99
	v_cmp_lt_i32_e32 vcc, v8, v92
	s_cselect_b64 s[18:19], -1, 0
	s_ashr_i32 s3, s2, 31
	v_cndmask_b32_e32 v8, v99, v8, vcc
	s_lshl_b64 s[8:9], s[2:3], 17
	v_lshlrev_b32_e32 v100, 2, v8
	v_xor_b32_e32 v8, 8, v99
	s_or_b32 s1, s8, s27
	v_cmp_lt_i32_e32 vcc, v8, v92
	s_add_u32 s1, s1, 0x80000
	s_addc_u32 s8, s9, 0
	v_cndmask_b32_e32 v8, v99, v8, vcc
	s_lshl_b32 s10, s27, 2
	s_mov_b32 s0, 0
	v_lshlrev_b32_e32 v101, 2, v8
	v_mov_b32_e32 v73, s8
	v_or_b32_e32 v72, s1, v80
	v_lshl_add_u64 v[74:75], v[84:85], 0, s[10:11]
	s_mov_b64 s[20:21], -1
	s_branch .LBB0_2753

; template <bool SAMPLE>
; __device__ __forceinline__ void mem_unit(const Params& p, int l, LAS unsigned char* lds, int unit, int tid, int wave, int lane) {
;     ...
;         int q16 = lane & 15, kq = lane >> 4; asm volatile("" : "+v"(q16), "+v"(kq));
;         size_t row; bool st;
;         if (!SAMPLE) { row = (size_t)b * 8192 + (qt * 4 + qq) * 128 + 16 * wave + q16; st = true; } else { row = (size_t)MP + 8 * b + (q16 & 7); st = q16 < 8; }
.LBB0_2761:
	s_and_b32 s0, s100, 15
	s_lshl_b32 s10, s0, 9
	s_lshl_b64 s[8:9], s[2:3], 13
	s_lshl_b32 s2, s27, 1
	s_add_u32 s0, s64, s2
	s_addc_u32 s1, s65, 0
	v_xor_b32_e32 v0, 16, v99
	s_add_u32 s2, s70, s2
	v_cmp_lt_i32_e32 vcc, v0, v92
	s_addc_u32 s3, s71, 0
	s_add_u32 s8, s4, s8
	v_cndmask_b32_e32 v0, v99, v0, vcc
	v_lshlrev_b32_e32 v82, 2, v0
	v_xor_b32_e32 v0, 32, v99
	v_cmp_lt_i32_e32 vcc, v0, v92
	s_addc_u32 s9, s5, s9
	s_add_u32 s10, s8, s10
	v_cndmask_b32_e32 v0, v99, v0, vcc
	v_lshlrev_b32_e32 v100, 2, v0
	s_addc_u32 s18, s9, 0
	s_mov_b64 s[8:9], 0
	s_waitcnt lgkmcnt(0)
	s_barrier
